# GDN scan: state/v_new fragment reads issued together with counted lgkmcnt waits (one exposed LDS latency per MFMA chain)
# baseline (speedup 1.0000x reference)
.LBB0_524:
	s_waitcnt lgkmcnt(0)
	s_barrier
	v_cndmask_b32_e64 v19, 0, 1, s[12:13]
	v_mov_b32_e32 v18, 0
	v_cmp_ne_u32_e64 s[0:1], 1, v19
	s_andn2_b64 vcc, exec, s[12:13]
	v_mov_b32_e32 v19, 0
	v_mov_b32_e32 v20, 0
	v_mov_b32_e32 v21, 0
	v_mov_b32_e32 v22, 0
	v_mov_b32_e32 v23, 0
	v_mov_b32_e32 v24, 0
	v_mov_b32_e32 v25, 0
	v_mov_b32_e32 v26, 0
	v_mov_b32_e32 v27, 0
	v_mov_b32_e32 v28, 0
	v_mov_b32_e32 v29, 0
	v_mov_b32_e32 v30, 0
	v_mov_b32_e32 v31, 0
	v_mov_b32_e32 v32, 0
	v_mov_b32_e32 v33, 0
	s_cbranch_vccnz .LBB0_527
	v_add_u32_e32 v38, v149, v148
	ds_read_b128 v[18:21], v38
	ds_read_b128 v[34:37], v38 offset:32
	ds_read_b128 v[40:43], v38 offset:64
	ds_read_b128 v[44:47], v38 offset:96
	ds_read_b128 v[240:243], v38 offset:128
	ds_read_b128 v[244:247], v38 offset:160
	ds_read_b128 v[248:251], v38 offset:192
	s_andn2_b64 vcc, exec, s[4:5]
	s_waitcnt lgkmcnt(5)
	v_mfma_f32_32x32x16_bf16 v[18:33], v[142:145], v[18:21], 0
	v_mfma_f32_32x32x16_bf16 v[18:33], v[138:141], v[34:37], v[18:33]
	ds_read_b128 v[34:37], v38 offset:224
	s_waitcnt lgkmcnt(5)
	v_mfma_f32_32x32x16_bf16 v[18:33], v[134:137], v[40:43], v[18:33]
	s_waitcnt lgkmcnt(4)
	v_mfma_f32_32x32x16_bf16 v[18:33], v[130:133], v[44:47], v[18:33]
	s_waitcnt lgkmcnt(3)
	v_mfma_f32_32x32x16_bf16 v[18:33], v[126:129], v[240:243], v[18:33]
	s_waitcnt lgkmcnt(2)
	v_mfma_f32_32x32x16_bf16 v[18:33], v[122:125], v[244:247], v[18:33]
	s_waitcnt lgkmcnt(1)
	v_mfma_f32_32x32x16_bf16 v[18:33], v[118:121], v[248:251], v[18:33]
	s_waitcnt lgkmcnt(0)
	v_mfma_f32_32x32x16_bf16 v[18:33], v[114:117], v[34:37], v[18:33]
	s_cbranch_vccnz .LBB0_527
	v_lshlrev_b32_e32 v34, 16, v216
	v_and_b32_e32 v35, 0xffff0000, v216
	v_lshlrev_b32_e32 v36, 16, v217
	v_and_b32_e32 v37, 0xffff0000, v217
	s_nop 6
	v_pk_add_f32 v[34:35], v[34:35], v[18:19] neg_lo:[0,1] neg_hi:[0,1]
	v_pk_add_f32 v[36:37], v[36:37], v[20:21] neg_lo:[0,1] neg_hi:[0,1]
	v_cvt_pk_bf16_f32 v34, v34, v35
	v_cvt_pk_bf16_f32 v35, v36, v37
	v_lshlrev_b32_e32 v36, 16, v214
	v_and_b32_e32 v37, 0xffff0000, v214
	v_lshlrev_b32_e32 v38, 16, v215
	v_and_b32_e32 v39, 0xffff0000, v215
	v_add_u32_e32 v40, v167, v146
	v_pk_add_f32 v[36:37], v[36:37], v[22:23] neg_lo:[0,1] neg_hi:[0,1]
	v_pk_add_f32 v[38:39], v[38:39], v[24:25] neg_lo:[0,1] neg_hi:[0,1]
	v_cvt_pk_bf16_f32 v36, v36, v37
	v_cvt_pk_bf16_f32 v37, v38, v39
	v_add_u32_e32 v40, 0x2000, v40
	ds_write2_b64 v40, v[34:35], v[36:37] offset0:64 offset1:66
	v_lshlrev_b32_e32 v34, 16, v212
	v_and_b32_e32 v35, 0xffff0000, v212
	v_lshlrev_b32_e32 v36, 16, v213
	v_and_b32_e32 v37, 0xffff0000, v213
	v_pk_add_f32 v[34:35], v[34:35], v[26:27] neg_lo:[0,1] neg_hi:[0,1]
	v_pk_add_f32 v[36:37], v[36:37], v[28:29] neg_lo:[0,1] neg_hi:[0,1]
	v_cvt_pk_bf16_f32 v34, v34, v35
	v_cvt_pk_bf16_f32 v35, v36, v37
	v_lshlrev_b32_e32 v36, 16, v210
	v_and_b32_e32 v37, 0xffff0000, v210
	v_lshlrev_b32_e32 v38, 16, v211
	v_and_b32_e32 v39, 0xffff0000, v211
	v_pk_add_f32 v[36:37], v[36:37], v[30:31] neg_lo:[0,1] neg_hi:[0,1]
	v_pk_add_f32 v[38:39], v[38:39], v[32:33] neg_lo:[0,1] neg_hi:[0,1]
	v_cvt_pk_bf16_f32 v36, v36, v37
	v_cvt_pk_bf16_f32 v37, v38, v39
	ds_write2_b64 v40, v[34:35], v[36:37] offset0:68 offset1:70
.LBB0_527:
	s_waitcnt lgkmcnt(0)
	s_barrier
	s_mov_b64 s[24:25], -1
	s_and_b64 vcc, exec, s[16:17]
	s_cbranch_vccz .LBB0_531
	v_mov_b64_e32 v[48:49], v[16:17]
	s_andn2_b64 vcc, exec, s[20:21]
	v_mov_b64_e32 v[46:47], v[14:15]
	v_mov_b64_e32 v[44:45], v[12:13]
	v_mov_b64_e32 v[42:43], v[10:11]
	v_mov_b64_e32 v[40:41], v[8:9]
	v_mov_b64_e32 v[38:39], v[6:7]
	v_mov_b64_e32 v[36:37], v[4:5]
	v_mov_b64_e32 v[34:35], v[2:3]
	s_cbranch_vccnz .LBB0_530
	v_add_u32_e32 v122, v153, v148
	ds_read_b128 v[114:117], v122 offset:8704
	ds_read_b128 v[118:121], v122 offset:8736
	ds_read_b128 v[240:243], v122 offset:8768
	ds_read_b128 v[244:247], v122 offset:8800
	v_pk_mul_f32 v[48:49], v[204:205], v[16:17] op_sel_hi:[0,1]
	v_pk_mul_f32 v[46:47], v[204:205], v[14:15] op_sel_hi:[0,1]
	v_pk_mul_f32 v[44:45], v[204:205], v[12:13] op_sel_hi:[0,1]
	v_pk_mul_f32 v[42:43], v[204:205], v[10:11] op_sel_hi:[0,1]
	v_pk_mul_f32 v[40:41], v[204:205], v[8:9] op_sel_hi:[0,1]
	v_pk_mul_f32 v[38:39], v[204:205], v[6:7] op_sel_hi:[0,1]
	v_pk_mul_f32 v[36:37], v[204:205], v[4:5] op_sel_hi:[0,1]
	v_pk_mul_f32 v[34:35], v[204:205], v[2:3] op_sel_hi:[0,1]
	s_waitcnt lgkmcnt(2)
	s_nop 0
	v_mfma_f32_32x32x16_bf16 v[34:49], v[110:113], v[114:117], v[34:49]
	v_mfma_f32_32x32x16_bf16 v[34:49], v[106:109], v[118:121], v[34:49]
	v_add_u32_e32 v122, v171, v146
	s_waitcnt lgkmcnt(0)
	v_mfma_f32_32x32x16_bf16 v[34:49], v[102:105], v[240:243], v[34:49]
	v_mfma_f32_32x32x16_bf16 v[34:49], v[98:101], v[244:247], v[34:49]
	s_nop 11
	v_cvt_pk_bf16_f32 v114, v34, v35
	v_cvt_pk_bf16_f32 v115, v36, v37
	v_cvt_pk_bf16_f32 v116, v38, v39
	v_cvt_pk_bf16_f32 v117, v40, v41
	v_cvt_pk_bf16_f32 v118, v42, v43
	v_cvt_pk_bf16_f32 v119, v44, v45
	v_cvt_pk_bf16_f32 v120, v46, v47
	v_cvt_pk_bf16_f32 v121, v48, v49
	ds_write2_b64 v122, v[114:115], v[116:117] offset1:2
	ds_write2_b64 v122, v[118:119], v[120:121] offset0:4 offset1:6

.LBB0_531:
	s_andn2_b64 vcc, exec, s[24:25]
	s_cbranch_vccnz .LBB0_533
	v_add_u32_e32 v38, v153, v148
	ds_read_b128 v[34:37], v38 offset:8704
	ds_read_b128 v[40:43], v38 offset:8736
	ds_read_b128 v[44:47], v38 offset:8768
	ds_read_b128 v[240:243], v38 offset:8800
	v_add_u32_e32 v38, v173, v179
	s_waitcnt lgkmcnt(3)
	v_mfma_f32_32x32x16_bf16 v[18:33], v[110:113], v[34:37], v[18:33]
	s_waitcnt lgkmcnt(2)
	v_mfma_f32_32x32x16_bf16 v[18:33], v[106:109], v[40:43], v[18:33]
	s_waitcnt lgkmcnt(1)
	v_mfma_f32_32x32x16_bf16 v[18:33], v[102:105], v[44:47], v[18:33]
	s_waitcnt lgkmcnt(0)
	v_mfma_f32_32x32x16_bf16 v[18:33], v[98:101], v[240:243], v[18:33]
	s_nop 11
	v_bfe_u32 v34, v18, 16, 1
	v_bfe_u32 v35, v19, 16, 1
	v_bfe_u32 v36, v20, 16, 1
	v_bfe_u32 v37, v21, 16, 1
	v_bfe_u32 v39, v22, 16, 1
	v_bfe_u32 v40, v23, 16, 1
	v_bfe_u32 v41, v24, 16, 1
	v_bfe_u32 v42, v25, 16, 1
	v_bfe_u32 v43, v26, 16, 1
	v_bfe_u32 v44, v27, 16, 1
	v_bfe_u32 v45, v28, 16, 1
	v_add3_u32 v18, v18, v34, s33
	v_add3_u32 v19, v19, v35, s33
	v_add3_u32 v20, v20, v36, s33
	v_add3_u32 v21, v21, v37, s33
	v_add3_u32 v22, v22, v39, s33
	v_add3_u32 v23, v23, v40, s33
	v_add3_u32 v24, v24, v41, s33
	v_add3_u32 v25, v25, v42, s33
	v_add3_u32 v26, v26, v43, s33
	v_add3_u32 v27, v27, v44, s33
	ds_write_b16_d16_hi v38, v18 offset:8192
	ds_write_b16_d16_hi v38, v19 offset:8272
	ds_write_b16_d16_hi v38, v20 offset:8352
	ds_write_b16_d16_hi v38, v21 offset:8432
	ds_write_b16_d16_hi v38, v22 offset:8832
	ds_write_b16_d16_hi v38, v23 offset:8912
	ds_write_b16_d16_hi v38, v24 offset:8992
	ds_write_b16_d16_hi v38, v25 offset:9072
	ds_write_b16_d16_hi v38, v26 offset:9472
	ds_write_b16_d16_hi v38, v27 offset:9552
	v_add3_u32 v18, v28, v45, s33
	ds_write_b16_d16_hi v38, v18 offset:9632
	v_bfe_u32 v18, v29, 16, 1
	v_add3_u32 v18, v29, v18, s33
	ds_write_b16_d16_hi v38, v18 offset:9712
	v_bfe_u32 v18, v30, 16, 1
	v_add3_u32 v18, v30, v18, s33
	ds_write_b16_d16_hi v38, v18 offset:10112
	v_bfe_u32 v18, v31, 16, 1
	v_add3_u32 v18, v31, v18, s33
	ds_write_b16_d16_hi v38, v18 offset:10192
	v_bfe_u32 v18, v32, 16, 1
	v_add3_u32 v18, v32, v18, s33
	ds_write_b16_d16_hi v38, v18 offset:10272
	v_bfe_u32 v18, v33, 16, 1
	v_add3_u32 v18, v33, v18, s33
	ds_write_b16_d16_hi v38, v18 offset:10352
	v_add_u32_e32 v24, v175, v183
	s_waitcnt lgkmcnt(0)
	ds_read_b128 v[18:21], v24 offset:8192
	v_lshl_add_u64 v[22:23], v[156:157], 0, s[8:9]
	v_or_b32_e32 v23, s73, v23
	v_or_b32_e32 v22, s72, v22
	v_lshlrev_b64 v[22:23], 11, v[22:23]
	v_lshl_add_u64 v[22:23], v[196:197], 0, v[22:23]
	s_waitcnt lgkmcnt(0)
	global_store_dwordx4 v[22:23], v[18:21], off
	ds_read_b128 v[18:21], v24 offset:9472
	v_lshl_add_u64 v[22:23], v[176:177], 0, s[8:9]
	v_or_b32_e32 v23, s73, v23
	v_or_b32_e32 v22, s72, v22
	v_lshlrev_b64 v[22:23], 11, v[22:23]
	v_lshl_add_u64 v[22:23], v[196:197], 0, v[22:23]
	s_waitcnt lgkmcnt(0)
	global_store_dwordx4 v[22:23], v[18:21], off
	s_waitcnt lgkmcnt(0)
	v_mov_b64_e32 v[48:49], v[16:17]
	v_mov_b64_e32 v[46:47], v[14:15]
	v_mov_b64_e32 v[44:45], v[12:13]
	v_mov_b64_e32 v[42:43], v[10:11]
	v_mov_b64_e32 v[40:41], v[8:9]
	v_mov_b64_e32 v[38:39], v[6:7]
	v_mov_b64_e32 v[36:37], v[4:5]
	v_mov_b64_e32 v[34:35], v[2:3]
